# pool GEMM loop: W fragments double-buffered, ds_reads one tile ahead
# baseline (speedup 1.0000x reference)
.LBB0_557:
	v_mov_b64_e32 v[34:35], s[28:29]
	v_lshl_or_b32 v104, s8, 8, v140
	v_mad_i64_i32 v[34:35], s[10:11], v32, s18, v[34:35]
	v_ashrrev_i32_e32 v105, 31, v104
	v_lshl_add_u64 v[106:107], v[34:35], 0, s[4:5]
	v_lshlrev_b64 v[34:35], 1, v[104:105]
	v_or_b32_e32 v108, 16, v104
	v_lshl_add_u64 v[36:37], v[106:107], 0, v[34:35]
	v_ashrrev_i32_e32 v109, 31, v108
	v_or_b32_e32 v110, 32, v104
	v_or_b32_e32 v112, 48, v104
	s_waitcnt lgkmcnt(0)
	s_barrier
	global_load_dwordx2 v[132:133], v[36:37], off
	v_lshl_add_u64 v[36:37], v[104:105], 2, s[60:61]
	v_lshl_add_u64 v[38:39], v[108:109], 1, v[106:107]
	v_ashrrev_i32_e32 v111, 31, v110
	v_ashrrev_i32_e32 v113, 31, v112
	global_load_dwordx4 v[60:63], v[36:37], off
	global_load_dwordx4 v[56:59], v[36:37], off offset:64
	v_lshl_add_u64 v[40:41], v[110:111], 1, v[106:107]
	v_lshl_add_u64 v[42:43], v[112:113], 1, v[106:107]
	global_load_dwordx2 v[130:131], v[38:39], off
	global_load_dwordx2 v[128:129], v[40:41], off
	global_load_dwordx2 v[126:127], v[42:43], off
	global_load_dwordx4 v[52:55], v[36:37], off offset:128
	global_load_dwordx4 v[48:51], v[36:37], off offset:192
	s_and_b32 s1, s19, 63
	v_lshl_add_u32 v36, s1, 7, v139
	v_ashrrev_i32_e32 v37, 31, v36
	v_lshlrev_b64 v[36:37], 12, v[36:37]
	v_lshlrev_b64 v[32:33], 12, v[32:33]
	v_lshl_add_u64 v[114:115], s[30:31], 0, v[32:33]
	v_lshl_add_u64 v[32:33], v[36:37], 0, v[34:35]
	v_lshl_add_u64 v[116:117], s[92:93], 0, v[32:33]
	s_mov_b64 s[10:11], 0
	s_mov_b32 s1, 64
	v_mov_b32_e32 v64, v143
	ds_read_b128 v[174:177], v64
	ds_read_b128 v[178:181], v64 offset:64
	ds_read_b128 v[182:185], v64 offset:128
	ds_read_b128 v[186:189], v64 offset:192
	ds_read_b128 v[190:193], v64 offset:256
	ds_read_b128 v[194:197], v64 offset:320
	ds_read_b128 v[198:201], v64 offset:384
	ds_read_b128 v[202:205], v64 offset:448
.LBB0_558:
	s_waitcnt lgkmcnt(0)
	ds_read_b128 v[206:209], v64 offset:8448
	ds_read_b128 v[210:213], v64 offset:8512
	ds_read_b128 v[214:217], v64 offset:8576
	ds_read_b128 v[218:221], v64 offset:8640
	ds_read_b128 v[222:225], v64 offset:8704
	ds_read_b128 v[226:229], v64 offset:8768
	ds_read_b128 v[230:233], v64 offset:8832
	ds_read_b128 v[234:237], v64 offset:8896
	v_add_u32_e32 v103, s1, v104
	v_subrev_u32_e32 v166, 64, v103
	s_cmpk_lg_i32 s10, 0x180
	s_cselect_b32 s12, s1, 0xc0
	v_add_u32_e32 v32, s12, v104
	v_add_u32_e32 v36, s12, v108
	v_add_u32_e32 v40, s12, v110
	s_waitcnt vmcnt(15)
	v_mfma_f32_16x16x32_bf16 v[162:165], v[174:177], v[0:3], 0
	v_add_u32_e32 v44, s12, v112
	v_ashrrev_i32_e32 v33, 31, v32
	v_ashrrev_i32_e32 v37, 31, v36
	s_waitcnt vmcnt(14)
	v_mfma_f32_16x16x32_bf16 v[162:165], v[178:181], v[4:7], v[162:165]
	v_ashrrev_i32_e32 v41, 31, v40
	v_ashrrev_i32_e32 v45, 31, v44
	v_ashrrev_i32_e32 v167, 31, v166
	v_lshl_add_u64 v[34:35], v[32:33], 1, v[106:107]
	v_lshl_add_u64 v[32:33], v[32:33], 2, s[60:61]
	v_lshl_add_u64 v[38:39], v[36:37], 1, v[106:107]
	v_lshl_add_u64 v[36:37], v[36:37], 2, s[60:61]
	s_waitcnt vmcnt(13)
	v_mfma_f32_16x16x32_bf16 v[162:165], v[182:185], v[8:11], v[162:165]
	v_lshl_add_u64 v[42:43], v[40:41], 1, v[106:107]
	v_lshl_add_u64 v[40:41], v[40:41], 2, s[60:61]
	v_lshl_add_u64 v[46:47], v[44:45], 1, v[106:107]
	v_lshl_add_u64 v[44:45], v[44:45], 2, s[60:61]
	global_load_dwordx2 v[118:119], v[34:35], off
	global_load_dwordx2 v[120:121], v[38:39], off
	s_waitcnt vmcnt(14)
	v_mfma_f32_16x16x32_bf16 v[162:165], v[186:189], v[12:15], v[162:165]
	global_load_dwordx4 v[32:35], v[32:33], off
	s_mov_b32 s12, 0xa800000
	global_load_dwordx4 v[36:39], v[36:37], off
	s_waitcnt vmcnt(15)
	v_mfma_f32_16x16x32_bf16 v[162:165], v[190:193], v[16:19], v[162:165]
	global_load_dwordx2 v[122:123], v[42:43], off
	global_load_dwordx2 v[124:125], v[46:47], off
	s_waitcnt vmcnt(16)
	v_mfma_f32_16x16x32_bf16 v[162:165], v[194:197], v[20:23], v[162:165]
	global_load_dwordx4 v[40:43], v[40:41], off
	s_nop 0
	global_load_dwordx4 v[44:47], v[44:45], off
	s_waitcnt vmcnt(17)
	v_mfma_f32_16x16x32_bf16 v[162:165], v[198:201], v[24:27], v[162:165]
	s_waitcnt vmcnt(16)
	v_mfma_f32_16x16x32_bf16 v[162:165], v[202:205], v[28:31], v[162:165]
	s_waitcnt vmcnt(15)
	v_lshlrev_b32_e32 v170, 16, v132
	v_mul_f32_e32 v103, 0xbfb8aa3b, v170
	v_exp_f32_e32 v103, v103
	v_and_b32_e32 v171, 0xffff0000, v132
	s_waitcnt vmcnt(14)
	s_nop 1
	v_pk_mul_f32 v[60:61], v[60:61], v[162:163]
	v_lshlrev_b32_e32 v132, 16, v133
	v_add_f32_e32 v103, 1.0, v103
	v_rcp_f32_e32 v172, v103
	v_mul_f32_e32 v103, 0xbfb8aa3b, v171
	v_exp_f32_e32 v103, v103
	v_and_b32_e32 v133, 0xffff0000, v133
	v_pk_mul_f32 v[62:63], v[62:63], v[164:165]
	v_add_f32_e32 v103, 1.0, v103
	v_rcp_f32_e32 v173, v103
	s_nop 0
	v_pk_mul_f32 v[162:163], v[172:173], v[170:171]
	s_nop 0
	v_pk_mul_f32 v[60:61], v[162:163], v[60:61]
	s_nop 0
	v_cvt_pk_bf16_f32 v60, v60, v61
	v_mul_f32_e32 v61, 0xbfb8aa3b, v132
	v_exp_f32_e32 v61, v61
	s_nop 0
	v_add_f32_e32 v61, 1.0, v61
	v_rcp_f32_e32 v162, v61
	v_mul_f32_e32 v61, 0xbfb8aa3b, v133
	v_exp_f32_e32 v61, v61
	s_nop 0
	v_add_f32_e32 v61, 1.0, v61
	v_rcp_f32_e32 v163, v61
	s_nop 0
	v_pk_mul_f32 v[132:133], v[162:163], v[132:133]
	s_nop 0
	v_pk_mul_f32 v[62:63], v[132:133], v[62:63]
	v_cvt_pk_bf16_f32 v61, v62, v63
	v_lshl_add_u64 v[62:63], v[166:167], 1, v[114:115]
	global_store_dwordx2 v[62:63], v[60:61], off offset:2048
	s_waitcnt lgkmcnt(0)
	ds_read_b128 v[174:177], v64 offset:16896
	ds_read_b128 v[178:181], v64 offset:16960
	ds_read_b128 v[182:185], v64 offset:17024
	ds_read_b128 v[186:189], v64 offset:17088
	ds_read_b128 v[190:193], v64 offset:17152
	ds_read_b128 v[194:197], v64 offset:17216
	ds_read_b128 v[198:201], v64 offset:17280
	ds_read_b128 v[202:205], v64 offset:17344
	v_mfma_f32_16x16x32_bf16 v[60:63], v[206:209], v[0:3], 0
	s_waitcnt vmcnt(13)
	v_lshlrev_b32_e32 v132, 16, v130
	v_and_b32_e32 v133, 0xffff0000, v130
	v_mul_f32_e32 v103, 0xbfb8aa3b, v132
	v_mfma_f32_16x16x32_bf16 v[60:63], v[210:213], v[4:7], v[60:63]
	v_exp_f32_e32 v103, v103
	v_mfma_f32_16x16x32_bf16 v[60:63], v[214:217], v[8:11], v[60:63]
	v_add_f32_e32 v103, 1.0, v103
	v_mfma_f32_16x16x32_bf16 v[60:63], v[218:221], v[12:15], v[60:63]
	v_mfma_f32_16x16x32_bf16 v[60:63], v[222:225], v[16:19], v[60:63]
	v_mfma_f32_16x16x32_bf16 v[60:63], v[226:229], v[20:23], v[60:63]
	v_mfma_f32_16x16x32_bf16 v[60:63], v[230:233], v[24:27], v[60:63]
	v_mfma_f32_16x16x32_bf16 v[60:63], v[234:237], v[28:31], v[60:63]
	v_rcp_f32_e32 v162, v103
	s_nop 6
	v_pk_mul_f32 v[56:57], v[56:57], v[60:61]
	v_mul_f32_e32 v60, 0xbfb8aa3b, v133
	v_exp_f32_e32 v60, v60
	v_pk_mul_f32 v[58:59], v[58:59], v[62:63]
	s_waitcnt vmcnt(12)
	v_lshlrev_b32_e32 v62, 16, v128
	v_and_b32_e32 v63, 0xffff0000, v128
	v_add_f32_e32 v60, 1.0, v60
	v_rcp_f32_e32 v163, v60
	v_mul_f32_e32 v103, 0xbfb8aa3b, v62
	v_exp_f32_e32 v103, v103
	s_waitcnt vmcnt(4)
	v_mov_b32_e32 v128, v122
	v_pk_mul_f32 v[60:61], v[162:163], v[132:133]
	v_add_f32_e32 v103, 1.0, v103
	v_pk_mul_f32 v[56:57], v[60:61], v[56:57]
	s_nop 0
	v_cvt_pk_bf16_f32 v60, v56, v57
	v_lshlrev_b32_e32 v56, 16, v131
	v_mul_f32_e32 v61, 0xbfb8aa3b, v56
	v_exp_f32_e32 v61, v61
	v_and_b32_e32 v57, 0xffff0000, v131
	v_add_f32_e32 v61, 1.0, v61
	v_rcp_f32_e32 v130, v61
	v_mul_f32_e32 v61, 0xbfb8aa3b, v57
	v_exp_f32_e32 v61, v61
	s_nop 0
	v_add_f32_e32 v61, 1.0, v61
	v_rcp_f32_e32 v131, v61
	s_nop 0
	v_pk_mul_f32 v[56:57], v[130:131], v[56:57]
	s_nop 0
	v_pk_mul_f32 v[56:57], v[56:57], v[58:59]
	v_cvt_pk_bf16_f32 v61, v56, v57
	v_lshl_add_u64 v[56:57], v[116:117], 0, s[10:11]
	v_add_co_u32_e32 v56, vcc, s12, v56
	s_add_u32 s10, s10, 0x80
	s_nop 0
	v_addc_co_u32_e32 v57, vcc, 0, v57, vcc
	global_store_dwordx2 v[56:57], v[60:61], off offset:2080
	s_waitcnt lgkmcnt(0)
	ds_read_b128 v[206:209], v64 offset:25344
	ds_read_b128 v[210:213], v64 offset:25408
	ds_read_b128 v[214:217], v64 offset:25472
	ds_read_b128 v[218:221], v64 offset:25536
	ds_read_b128 v[222:225], v64 offset:25600
	ds_read_b128 v[226:229], v64 offset:25664
	ds_read_b128 v[230:233], v64 offset:25728
	ds_read_b128 v[234:237], v64 offset:25792
	v_mfma_f32_16x16x32_bf16 v[58:61], v[174:177], v[0:3], 0
	s_addc_u32 s11, s11, 0
	s_add_i32 s1, s1, 64
	s_cmpk_lg_i32 s10, 0x200
	v_mfma_f32_16x16x32_bf16 v[58:61], v[178:181], v[4:7], v[58:61]
	v_mfma_f32_16x16x32_bf16 v[58:61], v[182:185], v[8:11], v[58:61]
	v_mfma_f32_16x16x32_bf16 v[58:61], v[186:189], v[12:15], v[58:61]
	v_mfma_f32_16x16x32_bf16 v[58:61], v[190:193], v[16:19], v[58:61]
	v_mfma_f32_16x16x32_bf16 v[58:61], v[194:197], v[20:23], v[58:61]
	v_mfma_f32_16x16x32_bf16 v[58:61], v[198:201], v[24:27], v[58:61]
	v_mfma_f32_16x16x32_bf16 v[58:61], v[202:205], v[28:31], v[58:61]
	v_rcp_f32_e32 v130, v103
	v_mov_b32_e32 v132, v118
	v_mov_b32_e32 v133, v119
	s_nop 4
	v_pk_mul_f32 v[52:53], v[52:53], v[58:59]
	v_mul_f32_e32 v58, 0xbfb8aa3b, v63
	v_exp_f32_e32 v58, v58
	v_pk_mul_f32 v[54:55], v[54:55], v[60:61]
	v_add_f32_e32 v58, 1.0, v58
	v_rcp_f32_e32 v131, v58
	s_nop 0
	v_pk_mul_f32 v[58:59], v[130:131], v[62:63]
	s_nop 0
	v_pk_mul_f32 v[52:53], v[58:59], v[52:53]
	v_lshlrev_b32_e32 v58, 16, v129
	v_cvt_pk_bf16_f32 v52, v52, v53
	v_mul_f32_e32 v53, 0xbfb8aa3b, v58
	v_exp_f32_e32 v53, v53
	v_and_b32_e32 v59, 0xffff0000, v129
	v_mov_b32_e32 v130, v120
	v_mov_b32_e32 v131, v121
	v_add_f32_e32 v53, 1.0, v53
	v_rcp_f32_e32 v62, v53
	v_mul_f32_e32 v53, 0xbfb8aa3b, v59
	v_exp_f32_e32 v53, v53
	v_mov_b32_e32 v129, v123
	v_add_f32_e32 v53, 1.0, v53
	v_rcp_f32_e32 v63, v53
	s_nop 0
	v_pk_mul_f32 v[58:59], v[62:63], v[58:59]
	s_nop 0
	v_pk_mul_f32 v[54:55], v[58:59], v[54:55]
	v_cvt_pk_bf16_f32 v53, v54, v55
	global_store_dwordx2 v[56:57], v[52:53], off offset:2112
	s_waitcnt lgkmcnt(0)
	v_add_u32_e32 v64, 0x8400, v64
	ds_read_b128 v[174:177], v64
	ds_read_b128 v[178:181], v64 offset:64
	ds_read_b128 v[182:185], v64 offset:128
	ds_read_b128 v[186:189], v64 offset:192
	ds_read_b128 v[190:193], v64 offset:256
	ds_read_b128 v[194:197], v64 offset:320
	ds_read_b128 v[198:201], v64 offset:384
	ds_read_b128 v[202:205], v64 offset:448
	v_mfma_f32_16x16x32_bf16 v[52:55], v[206:209], v[0:3], 0
	v_mov_b32_e32 v62, v34
	v_mov_b32_e32 v63, v35
	v_mfma_f32_16x16x32_bf16 v[52:55], v[210:213], v[4:7], v[52:55]
	v_mfma_f32_16x16x32_bf16 v[52:55], v[214:217], v[8:11], v[52:55]
	v_mfma_f32_16x16x32_bf16 v[52:55], v[218:221], v[12:15], v[52:55]
	v_mfma_f32_16x16x32_bf16 v[52:55], v[222:225], v[16:19], v[52:55]
	v_mfma_f32_16x16x32_bf16 v[52:55], v[226:229], v[20:23], v[52:55]
	v_mfma_f32_16x16x32_bf16 v[52:55], v[230:233], v[24:27], v[52:55]
	v_mfma_f32_16x16x32_bf16 v[52:55], v[234:237], v[28:31], v[52:55]
	v_lshlrev_b32_e32 v58, 16, v126
	v_and_b32_e32 v59, 0xffff0000, v126
	v_mul_f32_e32 v60, 0xbfb8aa3b, v58
	s_nop 4
	v_pk_mul_f32 v[48:49], v[48:49], v[52:53]
	v_mul_f32_e32 v52, 0xbfb8aa3b, v59
	v_exp_f32_e32 v60, v60
	v_exp_f32_e32 v52, v52
	v_pk_mul_f32 v[50:51], v[50:51], v[54:55]
	s_waitcnt vmcnt(5)
	v_mov_b32_e32 v126, v124
	v_add_f32_e32 v60, 1.0, v60
	v_add_f32_e32 v52, 1.0, v52
	v_rcp_f32_e32 v60, v60
	v_rcp_f32_e32 v61, v52
	s_waitcnt vmcnt(4)
	v_mov_b32_e32 v54, v42
	v_mov_b32_e32 v55, v43
	v_pk_mul_f32 v[52:53], v[60:61], v[58:59]
	s_nop 0
	v_pk_mul_f32 v[48:49], v[52:53], v[48:49]
	v_lshlrev_b32_e32 v52, 16, v127
	v_cvt_pk_bf16_f32 v48, v48, v49
	v_mul_f32_e32 v49, 0xbfb8aa3b, v52
	v_exp_f32_e32 v49, v49
	v_and_b32_e32 v53, 0xffff0000, v127
	v_mov_b32_e32 v127, v125
	v_mov_b32_e32 v60, v32
	v_add_f32_e32 v49, 1.0, v49
	v_rcp_f32_e32 v58, v49
	v_mul_f32_e32 v49, 0xbfb8aa3b, v53
	v_exp_f32_e32 v49, v49
	v_mov_b32_e32 v61, v33
	v_add_f32_e32 v49, 1.0, v49
	v_rcp_f32_e32 v59, v49
	s_nop 0
	v_pk_mul_f32 v[52:53], v[58:59], v[52:53]
	s_nop 0
	v_pk_mul_f32 v[50:51], v[52:53], v[50:51]
	v_mov_b32_e32 v58, v38
	v_cvt_pk_bf16_f32 v49, v50, v51
	global_store_dwordx2 v[56:57], v[48:49], off offset:2144
	v_mov_b32_e32 v56, v36
	v_mov_b32_e32 v57, v37
	v_mov_b32_e32 v59, v39
	v_mov_b32_e32 v52, v40
	v_mov_b32_e32 v53, v41
	s_waitcnt vmcnt(4)
	v_mov_b32_e32 v48, v44
	v_mov_b32_e32 v49, v45
	v_mov_b32_e32 v50, v46
	v_mov_b32_e32 v51, v47
	s_cbranch_scc1 .LBB0_558
	s_waitcnt lgkmcnt(0)
	s_cmp_lg_u32 s0, 0
	s_cbranch_scc1 .LBB0_554
	ds_read_b128 v[0:3], v160
	ds_read_b128 v[4:7], v160 offset:64
	ds_read_b128 v[8:11], v160 offset:128
	ds_read_b128 v[12:15], v160 offset:192
	ds_read_b128 v[16:19], v160 offset:256
	ds_read_b128 v[20:23], v160 offset:320
	ds_read_b128 v[24:27], v160 offset:384
	ds_read_b128 v[28:31], v160 offset:448
	ds_read_b128 v[32:35], v161
	ds_read_b128 v[36:39], v161 offset:64
	ds_read_b128 v[40:43], v161 offset:128
	ds_read_b128 v[44:47], v161 offset:192
	ds_read_b128 v[48:51], v161 offset:256
	ds_read_b128 v[52:55], v161 offset:320
	ds_read_b128 v[56:59], v161 offset:384
	ds_read_b128 v[60:63], v161 offset:448
	v_add_u32_e32 v110, v104, v141
	v_add_u32_e32 v112, v104, v142
	s_lshl_b64 s[0:1], s[8:9], 14
	v_ashrrev_i32_e32 v111, 31, v110
	v_ashrrev_i32_e32 v113, 31, v112
	v_lshl_add_u64 v[106:107], v[100:101], 0, s[0:1]
	v_lshl_add_u64 v[108:109], v[110:111], 2, s[60:61]
	v_lshl_add_u64 v[104:105], v[112:113], 2, s[60:61]
	s_mov_b32 s0, 0
	s_mov_b64 s[8:9], -1
	v_lshlrev_b64 v[110:111], 1, v[110:111]
	v_lshlrev_b64 v[112:113], 1, v[112:113]
